# early L2 writeback: one already-finished block per XCD issues buffer_wbl2 before the phase-end barrier of P1/P4/P5/P6
# baseline (speedup 1.0000x reference)
.Lcvt_done:
	s_sub_u32 s30, s2, 0x128
	s_cmp_lt_u32 s30, 8
	s_cbranch_scc0 .Lewb_p1
	s_waitcnt vmcnt(0)
	buffer_wbl2 sc1
	s_waitcnt vmcnt(0)

.Ltb_done:
	s_sub_u32 s30, s2, 0x80
	s_cmp_lt_u32 s30, 8
	s_cbranch_scc0 .Lewb_p4
	s_waitcnt vmcnt(0)
	buffer_wbl2 sc1
	s_waitcnt vmcnt(0)

.LBB0_811:
	s_sub_u32 s30, s2, 0x100
	s_cmp_lt_u32 s30, 8
	s_cbranch_scc0 .Lewb_p6
	s_waitcnt vmcnt(0)
	buffer_wbl2 sc1
	s_waitcnt vmcnt(0)
